# M1: prologue reorder + rotated k-loop (barrier ahead of last 8 MFMAs of previous slice, DMA interleaved)
# baseline (speedup 1.0000x reference)
.LBB0_1374:
	s_or_b64 exec, exec, s[4:5]
	v_lshl_add_u32 v183, v130, 2, v167
	s_waitcnt vmcnt(0)
	ds_write_b32 v183, v182
	v_and_b32_e32 v131, 63, v130
	s_mov_b32 s8, 0
	s_mov_b64 s[4:5], 0
	s_mov_b64 s[12:13], 0x6ff4080
	s_add_i32 s9, s8, 0x10000
	s_and_b32 s10, s9, 0x10000
	v_add_u32_e32 v246, s10, v128
	s_and_b32 s8, s8, 0x10000
	v_add_u32_e32 v153, s8, v152
	v_add_u32_e32 v154, s8, v151
	s_waitcnt vmcnt(0) lgkmcnt(0)
	s_barrier
	v_add_u32_e32 v181, v153, v149
	ds_read_b128 v[182:185], v181 offset:0x0
	ds_read_b128 v[186:189], v181 offset:0x1000
	ds_read_b128 v[190:193], v181 offset:0x2000
	ds_read_b128 v[194:197], v181 offset:0x3000
	v_add_u32_e32 v181, v154, v149
	ds_read_b128 v[198:201], v181 offset:0x0
	ds_read_b128 v[202:205], v181 offset:0x1000
	v_add_u32_e32 v181, v153, v148
	ds_read_b128 v[206:209], v181 offset:0x0
	ds_read_b128 v[210:213], v181 offset:0x1000
	ds_read_b128 v[214:217], v181 offset:0x2000
	ds_read_b128 v[218:221], v181 offset:0x3000
	v_add_u32_e32 v181, v154, v148
	ds_read_b128 v[222:225], v181 offset:0x0
	ds_read_b128 v[226:229], v181 offset:0x1000
	s_waitcnt lgkmcnt(6)
	v_mfma_f32_32x32x16_bf16 v[112:127], v[182:185], v[198:201], v[112:127]
	v_mfma_f32_32x32x16_bf16 v[48:63], v[182:185], v[202:205], v[48:63]
	v_lshl_add_u64 v[244:245], v[134:135], 0, s[4:5]
	v_lshl_add_u64 v[244:245], v[244:245], 0, s[90:91]
	v_readfirstlane_b32 s10, v246
	s_mov_b32 m0, s10
	s_nop 0
	global_load_lds_dwordx4 v[244:245], off
	v_mfma_f32_32x32x16_bf16 v[96:111], v[186:189], v[198:201], v[96:111]
	v_mfma_f32_32x32x16_bf16 v[32:47], v[186:189], v[202:205], v[32:47]
	v_add_u32_e32 v243, 0x2000, v246
	v_lshl_add_u64 v[244:245], v[134:135], 0, s[4:5]
	v_lshl_add_u64 v[244:245], v[244:245], 0, s[16:17]
	v_readfirstlane_b32 s10, v243
	s_mov_b32 m0, s10
	s_nop 0
	global_load_lds_dwordx4 v[244:245], off
	v_mfma_f32_32x32x16_bf16 v[80:95], v[190:193], v[198:201], v[80:95]
	v_mfma_f32_32x32x16_bf16 v[16:31], v[190:193], v[202:205], v[16:31]
	v_add_u32_e32 v243, 0x4000, v246
	v_lshl_add_u64 v[244:245], v[134:135], 0, s[4:5]
	v_lshl_add_u64 v[244:245], v[244:245], 0, s[20:21]
	v_readfirstlane_b32 s10, v243
	s_mov_b32 m0, s10
	s_nop 0
	global_load_lds_dwordx4 v[244:245], off
	v_mfma_f32_32x32x16_bf16 v[64:79], v[194:197], v[198:201], v[64:79]
	v_mfma_f32_32x32x16_bf16 v[0:15], v[194:197], v[202:205], v[0:15]
	v_add_u32_e32 v243, 0x6000, v246
	v_lshl_add_u64 v[244:245], v[134:135], 0, s[4:5]
	v_lshl_add_u64 v[244:245], v[244:245], 0, s[12:13]
	v_readfirstlane_b32 s10, v243
	s_mov_b32 m0, s10
	s_nop 0
	global_load_lds_dwordx4 v[244:245], off
	v_add_u32_e32 v181, v153, v147
	ds_read_b128 v[182:185], v181 offset:0x0
	ds_read_b128 v[186:189], v181 offset:0x1000
	ds_read_b128 v[190:193], v181 offset:0x2000
	ds_read_b128 v[194:197], v181 offset:0x3000
	v_add_u32_e32 v181, v154, v147
	ds_read_b128 v[198:201], v181 offset:0x0
	ds_read_b128 v[202:205], v181 offset:0x1000
	s_waitcnt lgkmcnt(6)
	v_mfma_f32_32x32x16_bf16 v[112:127], v[206:209], v[222:225], v[112:127]
	v_mfma_f32_32x32x16_bf16 v[48:63], v[206:209], v[226:229], v[48:63]
	v_add_u32_e32 v243, 0x8000, v246
	s_mov_b64 s[10:11], 0x1314080
	v_lshl_add_u64 v[244:245], v[132:133], 0, s[4:5]
	v_lshl_add_u64 v[244:245], v[244:245], 0, s[10:11]
	v_readfirstlane_b32 s10, v243
	s_mov_b32 m0, s10
	s_nop 0
	global_load_lds_dwordx4 v[244:245], off
	v_mfma_f32_32x32x16_bf16 v[96:111], v[210:213], v[222:225], v[96:111]
	v_mfma_f32_32x32x16_bf16 v[32:47], v[210:213], v[226:229], v[32:47]
	v_add_u32_e32 v243, 0xa000, v246
	s_mov_b64 s[10:11], 0x1334080
	v_lshl_add_u64 v[244:245], v[132:133], 0, s[4:5]
	v_lshl_add_u64 v[244:245], v[244:245], 0, s[10:11]
	v_readfirstlane_b32 s10, v243
	s_mov_b32 m0, s10
	s_nop 0
	global_load_lds_dwordx4 v[244:245], off
	v_mfma_f32_32x32x16_bf16 v[80:95], v[214:217], v[222:225], v[80:95]
	v_mfma_f32_32x32x16_bf16 v[16:31], v[214:217], v[226:229], v[16:31]
	v_add_u32_e32 v243, 0xc000, v246
	s_mov_b64 s[10:11], 0x1354080
	v_lshl_add_u64 v[244:245], v[132:133], 0, s[4:5]
	v_lshl_add_u64 v[244:245], v[244:245], 0, s[10:11]
	v_readfirstlane_b32 s10, v243
	s_mov_b32 m0, s10
	s_nop 0
	global_load_lds_dwordx4 v[244:245], off
	v_mfma_f32_32x32x16_bf16 v[64:79], v[218:221], v[222:225], v[64:79]
	v_mfma_f32_32x32x16_bf16 v[0:15], v[218:221], v[226:229], v[0:15]
	v_add_u32_e32 v243, 0xe000, v246
	s_mov_b64 s[10:11], 0x1374080
	v_lshl_add_u64 v[244:245], v[132:133], 0, s[4:5]
	v_lshl_add_u64 v[244:245], v[244:245], 0, s[10:11]
	v_readfirstlane_b32 s10, v243
	s_mov_b32 m0, s10
	s_nop 0
	global_load_lds_dwordx4 v[244:245], off
	v_add_u32_e32 v181, v153, v146
	ds_read_b128 v[206:209], v181 offset:0x0
	ds_read_b128 v[210:213], v181 offset:0x1000
	ds_read_b128 v[214:217], v181 offset:0x2000
	ds_read_b128 v[218:221], v181 offset:0x3000
	v_add_u32_e32 v181, v154, v146
	ds_read_b128 v[222:225], v181 offset:0x0
	ds_read_b128 v[226:229], v181 offset:0x1000
	s_waitcnt lgkmcnt(6)
	v_mfma_f32_32x32x16_bf16 v[112:127], v[182:185], v[198:201], v[112:127]
	v_mfma_f32_32x32x16_bf16 v[48:63], v[182:185], v[202:205], v[48:63]
	v_mfma_f32_32x32x16_bf16 v[96:111], v[186:189], v[198:201], v[96:111]
	v_mfma_f32_32x32x16_bf16 v[32:47], v[186:189], v[202:205], v[32:47]
	v_mfma_f32_32x32x16_bf16 v[80:95], v[190:193], v[198:201], v[80:95]
	v_mfma_f32_32x32x16_bf16 v[16:31], v[190:193], v[202:205], v[16:31]
	v_mfma_f32_32x32x16_bf16 v[64:79], v[194:197], v[198:201], v[64:79]
	v_mfma_f32_32x32x16_bf16 v[0:15], v[194:197], v[202:205], v[0:15]
	s_waitcnt lgkmcnt(0)
	s_add_u32 s4, s4, 0x80
	s_addc_u32 s5, s5, 0
	s_mov_b32 s8, s9
.LBB0_1375:
	s_add_i32 s9, s8, 0x10000
	s_and_b32 s10, s9, 0x10000
	v_add_u32_e32 v246, s10, v128
	s_and_b32 s8, s8, 0x10000
	v_add_u32_e32 v153, s8, v152
	v_add_u32_e32 v154, s8, v151
	s_waitcnt vmcnt(0) lgkmcnt(0)
	s_barrier
	v_add_u32_e32 v181, v153, v149
	ds_read_b128 v[182:185], v181 offset:0x0
	ds_read_b128 v[186:189], v181 offset:0x1000
	ds_read_b128 v[190:193], v181 offset:0x2000
	ds_read_b128 v[194:197], v181 offset:0x3000
	v_add_u32_e32 v181, v154, v149
	ds_read_b128 v[198:201], v181 offset:0x0
	ds_read_b128 v[202:205], v181 offset:0x1000
	v_mfma_f32_32x32x16_bf16 v[112:127], v[206:209], v[222:225], v[112:127]
	v_mfma_f32_32x32x16_bf16 v[48:63], v[206:209], v[226:229], v[48:63]
	v_lshl_add_u64 v[244:245], v[134:135], 0, s[4:5]
	v_lshl_add_u64 v[244:245], v[244:245], 0, s[90:91]
	v_readfirstlane_b32 s10, v246
	s_mov_b32 m0, s10
	s_nop 0
	global_load_lds_dwordx4 v[244:245], off
	v_mfma_f32_32x32x16_bf16 v[96:111], v[210:213], v[222:225], v[96:111]
	v_mfma_f32_32x32x16_bf16 v[32:47], v[210:213], v[226:229], v[32:47]
	v_add_u32_e32 v243, 0x2000, v246
	v_lshl_add_u64 v[244:245], v[134:135], 0, s[4:5]
	v_lshl_add_u64 v[244:245], v[244:245], 0, s[16:17]
	v_readfirstlane_b32 s10, v243
	s_mov_b32 m0, s10
	s_nop 0
	global_load_lds_dwordx4 v[244:245], off
	v_mfma_f32_32x32x16_bf16 v[80:95], v[214:217], v[222:225], v[80:95]
	v_mfma_f32_32x32x16_bf16 v[16:31], v[214:217], v[226:229], v[16:31]
	v_add_u32_e32 v243, 0x4000, v246
	v_lshl_add_u64 v[244:245], v[134:135], 0, s[4:5]
	v_lshl_add_u64 v[244:245], v[244:245], 0, s[20:21]
	v_readfirstlane_b32 s10, v243
	s_mov_b32 m0, s10
	s_nop 0
	global_load_lds_dwordx4 v[244:245], off
	v_mfma_f32_32x32x16_bf16 v[64:79], v[218:221], v[222:225], v[64:79]
	v_mfma_f32_32x32x16_bf16 v[0:15], v[218:221], v[226:229], v[0:15]
	v_add_u32_e32 v243, 0x6000, v246
	v_lshl_add_u64 v[244:245], v[134:135], 0, s[4:5]
	v_lshl_add_u64 v[244:245], v[244:245], 0, s[12:13]
	v_readfirstlane_b32 s10, v243
	s_mov_b32 m0, s10
	s_nop 0
	global_load_lds_dwordx4 v[244:245], off
	v_add_u32_e32 v181, v153, v148
	ds_read_b128 v[206:209], v181 offset:0x0
	ds_read_b128 v[210:213], v181 offset:0x1000
	ds_read_b128 v[214:217], v181 offset:0x2000
	ds_read_b128 v[218:221], v181 offset:0x3000
	v_add_u32_e32 v181, v154, v148
	ds_read_b128 v[222:225], v181 offset:0x0
	ds_read_b128 v[226:229], v181 offset:0x1000
	s_waitcnt lgkmcnt(6)
	v_mfma_f32_32x32x16_bf16 v[112:127], v[182:185], v[198:201], v[112:127]
	v_mfma_f32_32x32x16_bf16 v[48:63], v[182:185], v[202:205], v[48:63]
	v_add_u32_e32 v243, 0x8000, v246
	s_mov_b64 s[10:11], 0x1314080
	v_lshl_add_u64 v[244:245], v[132:133], 0, s[4:5]
	v_lshl_add_u64 v[244:245], v[244:245], 0, s[10:11]
	v_readfirstlane_b32 s10, v243
	s_mov_b32 m0, s10
	s_nop 0
	global_load_lds_dwordx4 v[244:245], off
	v_mfma_f32_32x32x16_bf16 v[96:111], v[186:189], v[198:201], v[96:111]
	v_mfma_f32_32x32x16_bf16 v[32:47], v[186:189], v[202:205], v[32:47]
	v_add_u32_e32 v243, 0xa000, v246
	s_mov_b64 s[10:11], 0x1334080
	v_lshl_add_u64 v[244:245], v[132:133], 0, s[4:5]
	v_lshl_add_u64 v[244:245], v[244:245], 0, s[10:11]
	v_readfirstlane_b32 s10, v243
	s_mov_b32 m0, s10
	s_nop 0
	global_load_lds_dwordx4 v[244:245], off
	v_mfma_f32_32x32x16_bf16 v[80:95], v[190:193], v[198:201], v[80:95]
	v_mfma_f32_32x32x16_bf16 v[16:31], v[190:193], v[202:205], v[16:31]
	v_add_u32_e32 v243, 0xc000, v246
	s_mov_b64 s[10:11], 0x1354080
	v_lshl_add_u64 v[244:245], v[132:133], 0, s[4:5]
	v_lshl_add_u64 v[244:245], v[244:245], 0, s[10:11]
	v_readfirstlane_b32 s10, v243
	s_mov_b32 m0, s10
	s_nop 0
	global_load_lds_dwordx4 v[244:245], off
	v_mfma_f32_32x32x16_bf16 v[64:79], v[194:197], v[198:201], v[64:79]
	v_mfma_f32_32x32x16_bf16 v[0:15], v[194:197], v[202:205], v[0:15]
	v_add_u32_e32 v243, 0xe000, v246
	s_mov_b64 s[10:11], 0x1374080
	v_lshl_add_u64 v[244:245], v[132:133], 0, s[4:5]
	v_lshl_add_u64 v[244:245], v[244:245], 0, s[10:11]
	v_readfirstlane_b32 s10, v243
	s_mov_b32 m0, s10
	s_nop 0
	global_load_lds_dwordx4 v[244:245], off
	v_add_u32_e32 v181, v153, v147
	ds_read_b128 v[182:185], v181 offset:0x0
	ds_read_b128 v[186:189], v181 offset:0x1000
	ds_read_b128 v[190:193], v181 offset:0x2000
	ds_read_b128 v[194:197], v181 offset:0x3000
	v_add_u32_e32 v181, v154, v147
	ds_read_b128 v[198:201], v181 offset:0x0
	ds_read_b128 v[202:205], v181 offset:0x1000
	s_waitcnt lgkmcnt(6)
	v_mfma_f32_32x32x16_bf16 v[112:127], v[206:209], v[222:225], v[112:127]
	v_mfma_f32_32x32x16_bf16 v[48:63], v[206:209], v[226:229], v[48:63]
	v_mfma_f32_32x32x16_bf16 v[96:111], v[210:213], v[222:225], v[96:111]
	v_mfma_f32_32x32x16_bf16 v[32:47], v[210:213], v[226:229], v[32:47]
	v_mfma_f32_32x32x16_bf16 v[80:95], v[214:217], v[222:225], v[80:95]
	v_mfma_f32_32x32x16_bf16 v[16:31], v[214:217], v[226:229], v[16:31]
	v_mfma_f32_32x32x16_bf16 v[64:79], v[218:221], v[222:225], v[64:79]
	v_mfma_f32_32x32x16_bf16 v[0:15], v[218:221], v[226:229], v[0:15]
	v_add_u32_e32 v181, v153, v146
	ds_read_b128 v[206:209], v181 offset:0x0
	ds_read_b128 v[210:213], v181 offset:0x1000
	ds_read_b128 v[214:217], v181 offset:0x2000
	ds_read_b128 v[218:221], v181 offset:0x3000
	v_add_u32_e32 v181, v154, v146
	ds_read_b128 v[222:225], v181 offset:0x0
	ds_read_b128 v[226:229], v181 offset:0x1000
	s_waitcnt lgkmcnt(6)
	v_mfma_f32_32x32x16_bf16 v[112:127], v[182:185], v[198:201], v[112:127]
	v_mfma_f32_32x32x16_bf16 v[48:63], v[182:185], v[202:205], v[48:63]
	v_mfma_f32_32x32x16_bf16 v[96:111], v[186:189], v[198:201], v[96:111]
	v_mfma_f32_32x32x16_bf16 v[32:47], v[186:189], v[202:205], v[32:47]
	v_mfma_f32_32x32x16_bf16 v[80:95], v[190:193], v[198:201], v[80:95]
	v_mfma_f32_32x32x16_bf16 v[16:31], v[190:193], v[202:205], v[16:31]
	v_mfma_f32_32x32x16_bf16 v[64:79], v[194:197], v[198:201], v[64:79]
	v_mfma_f32_32x32x16_bf16 v[0:15], v[194:197], v[202:205], v[0:15]
	s_waitcnt lgkmcnt(0)
	s_add_u32 s4, s4, 0x80
	s_addc_u32 s5, s5, 0
	s_mov_b32 s8, s9
	s_cmpk_lg_i32 s4, 0x780
	s_cbranch_scc1 .LBB0_1375
	s_and_b32 s8, s8, 0x10000
	v_add_u32_e32 v153, s8, v152
	v_add_u32_e32 v154, s8, v151
	s_waitcnt vmcnt(0) lgkmcnt(0)
	s_barrier
	v_add_u32_e32 v181, v153, v149
	ds_read_b128 v[182:185], v181 offset:0x0
	ds_read_b128 v[186:189], v181 offset:0x1000
	ds_read_b128 v[190:193], v181 offset:0x2000
	ds_read_b128 v[194:197], v181 offset:0x3000
	v_add_u32_e32 v181, v154, v149
	ds_read_b128 v[198:201], v181 offset:0x0
	ds_read_b128 v[202:205], v181 offset:0x1000
	v_mfma_f32_32x32x16_bf16 v[112:127], v[206:209], v[222:225], v[112:127]
	v_mfma_f32_32x32x16_bf16 v[48:63], v[206:209], v[226:229], v[48:63]
	v_mfma_f32_32x32x16_bf16 v[96:111], v[210:213], v[222:225], v[96:111]
	v_mfma_f32_32x32x16_bf16 v[32:47], v[210:213], v[226:229], v[32:47]
	v_mfma_f32_32x32x16_bf16 v[80:95], v[214:217], v[222:225], v[80:95]
	v_mfma_f32_32x32x16_bf16 v[16:31], v[214:217], v[226:229], v[16:31]
	v_mfma_f32_32x32x16_bf16 v[64:79], v[218:221], v[222:225], v[64:79]
	v_mfma_f32_32x32x16_bf16 v[0:15], v[218:221], v[226:229], v[0:15]
	v_add_u32_e32 v181, v153, v148
	ds_read_b128 v[206:209], v181 offset:0x0
	ds_read_b128 v[210:213], v181 offset:0x1000
	ds_read_b128 v[214:217], v181 offset:0x2000
	ds_read_b128 v[218:221], v181 offset:0x3000
	v_add_u32_e32 v181, v154, v148
	ds_read_b128 v[222:225], v181 offset:0x0
	ds_read_b128 v[226:229], v181 offset:0x1000
	s_waitcnt lgkmcnt(6)
	v_mfma_f32_32x32x16_bf16 v[112:127], v[182:185], v[198:201], v[112:127]
	v_mfma_f32_32x32x16_bf16 v[48:63], v[182:185], v[202:205], v[48:63]
	v_mfma_f32_32x32x16_bf16 v[96:111], v[186:189], v[198:201], v[96:111]
	v_mfma_f32_32x32x16_bf16 v[32:47], v[186:189], v[202:205], v[32:47]
	v_mfma_f32_32x32x16_bf16 v[80:95], v[190:193], v[198:201], v[80:95]
	v_mfma_f32_32x32x16_bf16 v[16:31], v[190:193], v[202:205], v[16:31]
	v_mfma_f32_32x32x16_bf16 v[64:79], v[194:197], v[198:201], v[64:79]
	v_mfma_f32_32x32x16_bf16 v[0:15], v[194:197], v[202:205], v[0:15]
	v_add_u32_e32 v181, v153, v147
	ds_read_b128 v[182:185], v181 offset:0x0
	ds_read_b128 v[186:189], v181 offset:0x1000
	ds_read_b128 v[190:193], v181 offset:0x2000
	ds_read_b128 v[194:197], v181 offset:0x3000
	v_add_u32_e32 v181, v154, v147
	ds_read_b128 v[198:201], v181 offset:0x0
	ds_read_b128 v[202:205], v181 offset:0x1000
	s_waitcnt lgkmcnt(6)
	v_mfma_f32_32x32x16_bf16 v[112:127], v[206:209], v[222:225], v[112:127]
	v_mfma_f32_32x32x16_bf16 v[48:63], v[206:209], v[226:229], v[48:63]
	v_mfma_f32_32x32x16_bf16 v[96:111], v[210:213], v[222:225], v[96:111]
	v_mfma_f32_32x32x16_bf16 v[32:47], v[210:213], v[226:229], v[32:47]
	v_mfma_f32_32x32x16_bf16 v[80:95], v[214:217], v[222:225], v[80:95]
	v_mfma_f32_32x32x16_bf16 v[16:31], v[214:217], v[226:229], v[16:31]
	v_mfma_f32_32x32x16_bf16 v[64:79], v[218:221], v[222:225], v[64:79]
	v_mfma_f32_32x32x16_bf16 v[0:15], v[218:221], v[226:229], v[0:15]
	v_add_u32_e32 v181, v153, v146
	ds_read_b128 v[206:209], v181 offset:0x0
	ds_read_b128 v[210:213], v181 offset:0x1000
	ds_read_b128 v[214:217], v181 offset:0x2000
	ds_read_b128 v[218:221], v181 offset:0x3000
	v_add_u32_e32 v181, v154, v146
	ds_read_b128 v[222:225], v181 offset:0x0
	ds_read_b128 v[226:229], v181 offset:0x1000
	s_waitcnt lgkmcnt(6)
	v_mfma_f32_32x32x16_bf16 v[112:127], v[182:185], v[198:201], v[112:127]
	v_mfma_f32_32x32x16_bf16 v[48:63], v[182:185], v[202:205], v[48:63]
	v_mfma_f32_32x32x16_bf16 v[96:111], v[186:189], v[198:201], v[96:111]
	v_mfma_f32_32x32x16_bf16 v[32:47], v[186:189], v[202:205], v[32:47]
	v_mfma_f32_32x32x16_bf16 v[80:95], v[190:193], v[198:201], v[80:95]
	v_mfma_f32_32x32x16_bf16 v[16:31], v[190:193], v[202:205], v[16:31]
	v_mfma_f32_32x32x16_bf16 v[64:79], v[194:197], v[198:201], v[64:79]
	v_mfma_f32_32x32x16_bf16 v[0:15], v[194:197], v[202:205], v[0:15]
	s_waitcnt lgkmcnt(0)
	v_mfma_f32_32x32x16_bf16 v[112:127], v[206:209], v[222:225], v[112:127]
	v_mfma_f32_32x32x16_bf16 v[48:63], v[206:209], v[226:229], v[48:63]
	v_mfma_f32_32x32x16_bf16 v[96:111], v[210:213], v[222:225], v[96:111]
	v_mfma_f32_32x32x16_bf16 v[32:47], v[210:213], v[226:229], v[32:47]
	v_mfma_f32_32x32x16_bf16 v[80:95], v[214:217], v[222:225], v[80:95]
	v_mfma_f32_32x32x16_bf16 v[16:31], v[214:217], v[226:229], v[16:31]
	v_mfma_f32_32x32x16_bf16 v[64:79], v[218:221], v[222:225], v[64:79]
	v_mfma_f32_32x32x16_bf16 v[0:15], v[218:221], v[226:229], v[0:15]
	v_lshrrev_b32_e32 v130, 3, v130
	v_lshlrev_b32_e32 v132, 2, v137
	v_lshlrev_b32_e32 v133, 2, v144
	s_mov_b32 s4, 0x24000
	v_and_b32_e32 v147, 4, v130
	v_add3_u32 v146, v132, v133, s4
	v_lshlrev_b32_e32 v130, 2, v136
	v_lshlrev_b32_e32 v132, 2, v147
	s_mov_b32 s4, 0x24400
	s_barrier
	v_add3_u32 v130, v130, v132, s4
	ds_read_b32 v148, v146
	ds_read_b128 v[132:135], v130
	s_movk_i32 s4, 0x2400
	v_mul_lo_u32 v145, v145, s4
	s_movk_i32 s4, 0x110
	v_mad_u32_u24 v144, v144, s4, v145
	s_waitcnt lgkmcnt(0)
	v_fma_f32 v112, v112, v148, v132
	v_fma_f32 v113, v113, v148, v133
	v_max_f32_e32 v112, 0, v112
	v_max_f32_e32 v113, 0, v113
	v_fma_f32 v114, v114, v148, v134
	v_fmac_f32_e32 v135, v115, v148
	v_max_f32_e32 v132, 0, v114
	v_max_f32_e32 v115, 0, v135
	v_mul_f32_e32 v112, v112, v112
	v_mul_f32_e32 v113, v113, v113
	v_cvt_pk_bf16_f32 v114, v112, v113
	v_mul_f32_e32 v112, v132, v132
	v_mul_f32_e32 v113, v115, v115
	v_cvt_pk_bf16_f32 v115, v112, v113
	v_lshl_or_b32 v112, v147, 1, v144
	ds_write_b64 v112, v[114:115]
	ds_read_b128 v[132:135], v130 offset:32
	v_and_b32_e32 v128, 0xf0, v128
	s_add_i32 s7, s7, s38
	s_cmpk_gt_i32 s7, 0x2ff
	s_waitcnt lgkmcnt(0)
	v_fma_f32 v113, v116, v148, v132
	v_fma_f32 v114, v117, v148, v133
	v_max_f32_e32 v113, 0, v113
	v_max_f32_e32 v114, 0, v114
	v_fma_f32 v115, v118, v148, v134
	v_fmac_f32_e32 v135, v119, v148
	v_max_f32_e32 v115, 0, v115
	v_max_f32_e32 v116, 0, v135
	v_mul_f32_e32 v113, v113, v113
	v_mul_f32_e32 v114, v114, v114
	v_cvt_pk_bf16_f32 v114, v113, v114
	v_mul_f32_e32 v113, v115, v115
	v_mul_f32_e32 v115, v116, v116
	v_cvt_pk_bf16_f32 v115, v113, v115
	ds_write_b64 v112, v[114:115] offset:16
	ds_read_b128 v[114:117], v130 offset:64
	s_waitcnt lgkmcnt(0)
	v_fma_f32 v113, v120, v148, v114
	v_fma_f32 v114, v121, v148, v115
	v_max_f32_e32 v113, 0, v113
	v_max_f32_e32 v114, 0, v114
	v_fma_f32 v115, v122, v148, v116
	v_fmac_f32_e32 v117, v123, v148
	v_max_f32_e32 v115, 0, v115
	v_max_f32_e32 v116, 0, v117
	v_mul_f32_e32 v113, v113, v113
	v_mul_f32_e32 v114, v114, v114
	v_cvt_pk_bf16_f32 v114, v113, v114
	v_mul_f32_e32 v113, v115, v115
	v_mul_f32_e32 v115, v116, v116
	v_cvt_pk_bf16_f32 v115, v113, v115
	ds_write_b64 v112, v[114:115] offset:32
	ds_read_b128 v[114:117], v130 offset:96
	s_waitcnt lgkmcnt(0)
	v_fma_f32 v113, v124, v148, v114
	v_fma_f32 v114, v125, v148, v115
	v_max_f32_e32 v113, 0, v113
	v_max_f32_e32 v114, 0, v114
	v_fma_f32 v115, v126, v148, v116
	v_fmac_f32_e32 v117, v127, v148
	v_max_f32_e32 v115, 0, v115
	v_max_f32_e32 v116, 0, v117
	v_mul_f32_e32 v113, v113, v113
	v_mul_f32_e32 v114, v114, v114
	v_cvt_pk_bf16_f32 v114, v113, v114
	v_mul_f32_e32 v113, v115, v115
	v_mul_f32_e32 v115, v116, v116
	v_cvt_pk_bf16_f32 v115, v113, v115
	ds_write_b64 v112, v[114:115] offset:48
	ds_read_b128 v[114:117], v130 offset:128
	s_waitcnt lgkmcnt(0)
	v_fma_f32 v96, v96, v148, v114
	v_fma_f32 v97, v97, v148, v115
	v_max_f32_e32 v96, 0, v96
	v_max_f32_e32 v97, 0, v97
	v_fma_f32 v98, v98, v148, v116
	v_fmac_f32_e32 v117, v99, v148
	v_max_f32_e32 v98, 0, v98
	v_max_f32_e32 v99, 0, v117
	v_mul_f32_e32 v96, v96, v96
	v_mul_f32_e32 v97, v97, v97
	v_cvt_pk_bf16_f32 v96, v96, v97
	v_mul_f32_e32 v97, v98, v98
	v_mul_f32_e32 v98, v99, v99
	v_cvt_pk_bf16_f32 v97, v97, v98
	ds_write_b64 v112, v[96:97] offset:64
	ds_read_b128 v[96:99], v130 offset:160
	s_waitcnt lgkmcnt(0)
	v_fma_f32 v96, v100, v148, v96
	v_fma_f32 v97, v101, v148, v97
	v_max_f32_e32 v96, 0, v96
	v_max_f32_e32 v97, 0, v97
	v_fma_f32 v98, v102, v148, v98
	v_fmac_f32_e32 v99, v103, v148
	v_max_f32_e32 v98, 0, v98
	v_max_f32_e32 v99, 0, v99
	v_mul_f32_e32 v96, v96, v96
	v_mul_f32_e32 v97, v97, v97
	v_cvt_pk_bf16_f32 v96, v96, v97
	v_mul_f32_e32 v97, v98, v98
	v_mul_f32_e32 v98, v99, v99
	v_cvt_pk_bf16_f32 v97, v97, v98
	ds_write_b64 v112, v[96:97] offset:80
	ds_read_b128 v[96:99], v130 offset:192
	v_add_u32_e32 v102, s2, v136
	v_ashrrev_i32_e32 v103, 31, v102
	s_waitcnt lgkmcnt(0)
	v_fma_f32 v96, v104, v148, v96
	v_fma_f32 v97, v105, v148, v97
	v_max_f32_e32 v96, 0, v96
	v_max_f32_e32 v97, 0, v97
	v_fma_f32 v98, v106, v148, v98
	v_fmac_f32_e32 v99, v107, v148
	v_max_f32_e32 v98, 0, v98
	v_max_f32_e32 v99, 0, v99
	v_mul_f32_e32 v96, v96, v96
	v_mul_f32_e32 v97, v97, v97
	v_cvt_pk_bf16_f32 v96, v96, v97
	v_mul_f32_e32 v97, v98, v98
	v_mul_f32_e32 v98, v99, v99
	v_cvt_pk_bf16_f32 v97, v97, v98
	ds_write_b64 v112, v[96:97] offset:96
	ds_read_b128 v[96:99], v130 offset:224
	v_add_u32_e32 v106, s3, v137
	v_lshrrev_b32_e32 v107, 4, v131
	s_waitcnt lgkmcnt(0)
	v_fma_f32 v96, v108, v148, v96
	v_fma_f32 v97, v109, v148, v97
	v_max_f32_e32 v96, 0, v96
	v_max_f32_e32 v97, 0, v97
	v_fma_f32 v98, v110, v148, v98
	v_fmac_f32_e32 v99, v111, v148
	v_max_f32_e32 v98, 0, v98
	v_max_f32_e32 v99, 0, v99
	v_mul_f32_e32 v96, v96, v96
	v_mul_f32_e32 v97, v97, v97
	v_cvt_pk_bf16_f32 v96, v96, v97
	v_mul_f32_e32 v97, v98, v98
	v_mul_f32_e32 v98, v99, v99
	v_cvt_pk_bf16_f32 v97, v97, v98
	ds_write_b64 v112, v[96:97] offset:112
	ds_read_b128 v[96:99], v130 offset:256
	s_waitcnt lgkmcnt(0)
	v_fma_f32 v80, v80, v148, v96
	v_fma_f32 v81, v81, v148, v97
	v_max_f32_e32 v80, 0, v80
	v_max_f32_e32 v81, 0, v81
	v_fma_f32 v82, v82, v148, v98
	v_fmac_f32_e32 v99, v83, v148
	v_max_f32_e32 v82, 0, v82
	v_max_f32_e32 v83, 0, v99
	v_mul_f32_e32 v80, v80, v80
	v_mul_f32_e32 v81, v81, v81
	v_cvt_pk_bf16_f32 v80, v80, v81
	v_mul_f32_e32 v81, v82, v82
	v_mul_f32_e32 v82, v83, v83
	v_cvt_pk_bf16_f32 v81, v81, v82
	ds_write_b64 v112, v[80:81] offset:128
	ds_read_b128 v[80:83], v130 offset:288
	s_waitcnt lgkmcnt(0)
	v_fma_f32 v80, v84, v148, v80
	v_fma_f32 v81, v85, v148, v81
	v_max_f32_e32 v80, 0, v80
	v_max_f32_e32 v81, 0, v81
	v_fma_f32 v82, v86, v148, v82
	v_fmac_f32_e32 v83, v87, v148
	v_max_f32_e32 v82, 0, v82
	v_max_f32_e32 v83, 0, v83
	v_mul_f32_e32 v80, v80, v80
	v_mul_f32_e32 v81, v81, v81
	v_cvt_pk_bf16_f32 v80, v80, v81
	v_mul_f32_e32 v81, v82, v82
	v_mul_f32_e32 v82, v83, v83
	v_cvt_pk_bf16_f32 v81, v81, v82
	ds_write_b64 v112, v[80:81] offset:144
	ds_read_b128 v[80:83], v130 offset:320
	s_waitcnt lgkmcnt(0)
	v_fma_f32 v80, v88, v148, v80
	v_fma_f32 v81, v89, v148, v81
	v_max_f32_e32 v80, 0, v80
	v_max_f32_e32 v81, 0, v81
	v_fma_f32 v82, v90, v148, v82
	v_fmac_f32_e32 v83, v91, v148
	v_max_f32_e32 v82, 0, v82
	v_max_f32_e32 v83, 0, v83
	v_mul_f32_e32 v80, v80, v80
	v_mul_f32_e32 v81, v81, v81
	v_cvt_pk_bf16_f32 v80, v80, v81
	v_mul_f32_e32 v81, v82, v82
	v_mul_f32_e32 v82, v83, v83
	v_cvt_pk_bf16_f32 v81, v81, v82
	ds_write_b64 v112, v[80:81] offset:160
	ds_read_b128 v[80:83], v130 offset:352
	s_waitcnt lgkmcnt(0)
	v_fma_f32 v80, v92, v148, v80
	v_fma_f32 v81, v93, v148, v81
	v_max_f32_e32 v80, 0, v80
	v_max_f32_e32 v81, 0, v81
	v_fma_f32 v82, v94, v148, v82
	v_fmac_f32_e32 v83, v95, v148
	v_max_f32_e32 v82, 0, v82
	v_max_f32_e32 v83, 0, v83
	v_mul_f32_e32 v80, v80, v80
	v_mul_f32_e32 v81, v81, v81
	v_cvt_pk_bf16_f32 v80, v80, v81
	v_mul_f32_e32 v81, v82, v82
	v_mul_f32_e32 v82, v83, v83
	v_cvt_pk_bf16_f32 v81, v81, v82
	ds_write_b64 v112, v[80:81] offset:176
	ds_read_b128 v[80:83], v130 offset:384
	s_waitcnt lgkmcnt(0)
	v_fma_f32 v64, v64, v148, v80
	v_fma_f32 v65, v65, v148, v81
	v_max_f32_e32 v64, 0, v64
	v_max_f32_e32 v65, 0, v65
	v_fma_f32 v66, v66, v148, v82
	v_fmac_f32_e32 v83, v67, v148
	v_max_f32_e32 v66, 0, v66
	v_max_f32_e32 v67, 0, v83
	v_mul_f32_e32 v64, v64, v64
	v_mul_f32_e32 v65, v65, v65
	v_cvt_pk_bf16_f32 v64, v64, v65
	v_mul_f32_e32 v65, v66, v66
	v_mul_f32_e32 v66, v67, v67
	v_cvt_pk_bf16_f32 v65, v65, v66
	ds_write_b64 v112, v[64:65] offset:192
	ds_read_b128 v[64:67], v130 offset:416
	s_waitcnt lgkmcnt(0)
	v_fma_f32 v64, v68, v148, v64
	v_fma_f32 v65, v69, v148, v65
	v_max_f32_e32 v64, 0, v64
	v_max_f32_e32 v65, 0, v65
	v_fma_f32 v66, v70, v148, v66
	v_fmac_f32_e32 v67, v71, v148
	v_max_f32_e32 v66, 0, v66
	v_max_f32_e32 v67, 0, v67
	v_mul_f32_e32 v64, v64, v64
	v_mul_f32_e32 v65, v65, v65
	v_cvt_pk_bf16_f32 v64, v64, v65
	v_mul_f32_e32 v65, v66, v66
	v_mul_f32_e32 v66, v67, v67
	v_cvt_pk_bf16_f32 v65, v65, v66
	ds_write_b64 v112, v[64:65] offset:208
	ds_read_b128 v[64:67], v130 offset:448
	v_or_b32_e32 v68, v145, v128
	v_mad_u32_u24 v108, v107, s4, v68
	s_waitcnt lgkmcnt(0)
	v_fma_f32 v64, v72, v148, v64
	v_fma_f32 v65, v73, v148, v65
	v_max_f32_e32 v64, 0, v64
	v_max_f32_e32 v65, 0, v65
	v_fma_f32 v66, v74, v148, v66
	v_fmac_f32_e32 v67, v75, v148
	v_max_f32_e32 v66, 0, v66
	v_max_f32_e32 v67, 0, v67
	v_mul_f32_e32 v64, v64, v64
	v_mul_f32_e32 v65, v65, v65
	v_cvt_pk_bf16_f32 v64, v64, v65
	v_mul_f32_e32 v65, v66, v66
	v_mul_f32_e32 v66, v67, v67
	v_cvt_pk_bf16_f32 v65, v65, v66
	ds_write_b64 v112, v[64:65] offset:224
	ds_read_b128 v[64:67], v130 offset:480
	s_waitcnt lgkmcnt(0)
	v_fma_f32 v64, v76, v148, v64
	v_fma_f32 v65, v77, v148, v65
	v_max_f32_e32 v64, 0, v64
	v_max_f32_e32 v65, 0, v65
	v_fma_f32 v66, v78, v148, v66
	v_fmac_f32_e32 v67, v79, v148
	v_max_f32_e32 v66, 0, v66
	v_max_f32_e32 v67, 0, v67
	v_mul_f32_e32 v64, v64, v64
	v_mul_f32_e32 v65, v65, v65
	v_cvt_pk_bf16_f32 v64, v64, v65
	v_mul_f32_e32 v65, v66, v66
	v_mul_f32_e32 v66, v67, v67
	v_cvt_pk_bf16_f32 v65, v65, v66
	ds_write_b64 v112, v[64:65] offset:240
	v_or_b32_e32 v64, v106, v107
	v_or_b32_e32 v77, 4, v107
	v_ashrrev_i32_e32 v65, 31, v64
	v_mad_u32_u24 v76, v77, s4, v68
	v_lshlrev_b64 v[104:105], 13, v[64:65]
	ds_read_b128 v[78:81], v76 offset:1088
	ds_read_b128 v[82:85], v76 offset:2176
	ds_read_b128 v[86:89], v108
	ds_read_b32 v109, v146 offset:128
	ds_read_b128 v[90:93], v76
	ds_read_b128 v[94:97], v130
	ds_read_b128 v[98:101], v76 offset:3264
	ds_read_b128 v[72:75], v76 offset:4352
	ds_read_b128 v[68:71], v76 offset:5440
	ds_read_b128 v[64:67], v76 offset:6528
	s_waitcnt lgkmcnt(4)
	v_fma_f32 v48, v48, v109, v94
	v_fma_f32 v49, v49, v109, v95
	v_max_f32_e32 v48, 0, v48
	v_max_f32_e32 v49, 0, v49
	v_fma_f32 v50, v50, v109, v96
	v_fmac_f32_e32 v97, v51, v109
	v_max_f32_e32 v50, 0, v50
	v_max_f32_e32 v51, 0, v97
	v_mul_f32_e32 v48, v48, v48
	v_mul_f32_e32 v49, v49, v49
	v_cvt_pk_bf16_f32 v48, v48, v49
	v_mul_f32_e32 v49, v50, v50
	v_mul_f32_e32 v50, v51, v51
	v_cvt_pk_bf16_f32 v49, v49, v50
	ds_write_b64 v112, v[48:49]
	ds_read_b128 v[94:97], v130 offset:32
	v_lshl_add_u64 v[50:51], s[42:43], 0, v[104:105]
	v_lshlrev_b64 v[48:49], 1, v[102:103]
	v_lshl_add_u64 v[50:51], v[50:51], 0, v[48:49]
	v_lshl_add_u64 v[102:103], v[50:51], 0, v[128:129]
	s_waitcnt lgkmcnt(0)
	v_fma_f32 v50, v52, v109, v94
	v_fma_f32 v51, v53, v109, v95
	v_max_f32_e32 v50, 0, v50
	v_max_f32_e32 v51, 0, v51
	v_fma_f32 v52, v54, v109, v96
	v_fmac_f32_e32 v97, v55, v109
	v_max_f32_e32 v52, 0, v52
	v_max_f32_e32 v53, 0, v97
	v_mul_f32_e32 v50, v50, v50
	v_mul_f32_e32 v51, v51, v51
	v_cvt_pk_bf16_f32 v50, v50, v51
	v_mul_f32_e32 v51, v52, v52
	v_mul_f32_e32 v52, v53, v53
	v_cvt_pk_bf16_f32 v51, v51, v52
	ds_write_b64 v112, v[50:51] offset:16
	ds_read_b128 v[50:53], v130 offset:64
	v_or_b32_e32 v54, v106, v77
	v_ashrrev_i32_e32 v55, 31, v54
	v_lshlrev_b64 v[54:55], 13, v[54:55]
	v_lshl_add_u64 v[54:55], s[42:43], 0, v[54:55]
	s_waitcnt lgkmcnt(0)
	v_fma_f32 v50, v56, v109, v50
	v_fma_f32 v51, v57, v109, v51
	v_max_f32_e32 v50, 0, v50
	v_max_f32_e32 v51, 0, v51
	v_fma_f32 v52, v58, v109, v52
	v_fmac_f32_e32 v53, v59, v109
	v_max_f32_e32 v52, 0, v52
	v_max_f32_e32 v53, 0, v53
	v_mul_f32_e32 v50, v50, v50
	v_mul_f32_e32 v51, v51, v51
	v_cvt_pk_bf16_f32 v50, v50, v51
	v_mul_f32_e32 v51, v52, v52
	v_mul_f32_e32 v52, v53, v53
	v_cvt_pk_bf16_f32 v51, v51, v52
	ds_write_b64 v112, v[50:51] offset:32
	ds_read_b128 v[50:53], v130 offset:96
	v_or_b32_e32 v56, 8, v107
	v_lshl_add_u64 v[54:55], v[54:55], 0, v[48:49]
	v_lshl_add_u64 v[54:55], v[54:55], 0, v[128:129]
	global_store_dwordx4 v[54:55], v[90:93], off
	s_waitcnt lgkmcnt(0)
	v_fma_f32 v50, v60, v109, v50
	v_fma_f32 v51, v61, v109, v51
	v_max_f32_e32 v50, 0, v50
	v_max_f32_e32 v51, 0, v51
	v_fma_f32 v52, v62, v109, v52
	v_fmac_f32_e32 v53, v63, v109
	v_max_f32_e32 v52, 0, v52
	v_max_f32_e32 v53, 0, v53
	v_mul_f32_e32 v50, v50, v50
	v_mul_f32_e32 v51, v51, v51
	v_cvt_pk_bf16_f32 v50, v50, v51
	v_mul_f32_e32 v51, v52, v52
	v_mul_f32_e32 v52, v53, v53
	v_cvt_pk_bf16_f32 v51, v51, v52
	ds_write_b64 v112, v[50:51] offset:48
	ds_read_b128 v[50:53], v130 offset:128
	v_or_b32_e32 v54, v106, v56
	v_ashrrev_i32_e32 v55, 31, v54
	v_lshlrev_b64 v[54:55], 13, v[54:55]
	global_store_dwordx4 v[102:103], v[86:89], off
	s_waitcnt lgkmcnt(0)
	v_fma_f32 v32, v32, v109, v50
	v_fma_f32 v33, v33, v109, v51
	v_max_f32_e32 v32, 0, v32
	v_max_f32_e32 v33, 0, v33
	v_fma_f32 v34, v34, v109, v52
	v_fmac_f32_e32 v53, v35, v109
	v_max_f32_e32 v34, 0, v34
	v_max_f32_e32 v35, 0, v53
	v_mul_f32_e32 v32, v32, v32
	v_mul_f32_e32 v33, v33, v33
	v_cvt_pk_bf16_f32 v32, v32, v33
	v_mul_f32_e32 v33, v34, v34
	v_mul_f32_e32 v34, v35, v35
	v_cvt_pk_bf16_f32 v33, v33, v34
	ds_write_b64 v112, v[32:33] offset:64
	ds_read_b128 v[32:35], v130 offset:160
	v_lshl_add_u64 v[50:51], s[42:43], 0, v[54:55]
	v_lshl_add_u64 v[50:51], v[50:51], 0, v[48:49]
	v_lshl_add_u64 v[50:51], v[50:51], 0, v[128:129]
	global_store_dwordx4 v[50:51], v[78:81], off
	s_waitcnt lgkmcnt(0)
	v_fma_f32 v32, v36, v109, v32
	v_fma_f32 v33, v37, v109, v33
	v_max_f32_e32 v32, 0, v32
	v_max_f32_e32 v33, 0, v33
	v_fma_f32 v34, v38, v109, v34
	v_fmac_f32_e32 v35, v39, v109
	v_max_f32_e32 v34, 0, v34
	v_max_f32_e32 v35, 0, v35
	v_mul_f32_e32 v32, v32, v32
	v_mul_f32_e32 v33, v33, v33
	v_cvt_pk_bf16_f32 v32, v32, v33
	v_mul_f32_e32 v33, v34, v34
	v_mul_f32_e32 v34, v35, v35
	v_cvt_pk_bf16_f32 v33, v33, v34
	ds_write_b64 v112, v[32:33] offset:80
	ds_read_b128 v[32:35], v130 offset:192
	v_or_b32_e32 v38, 12, v107
	v_or_b32_e32 v39, 16, v107
	v_or_b32_e32 v36, v106, v38
	v_ashrrev_i32_e32 v37, 31, v36
	s_waitcnt lgkmcnt(0)
	v_fma_f32 v32, v40, v109, v32
	v_fma_f32 v33, v41, v109, v33
	v_max_f32_e32 v32, 0, v32
	v_max_f32_e32 v33, 0, v33
	v_fma_f32 v34, v42, v109, v34
	v_fmac_f32_e32 v35, v43, v109
	v_max_f32_e32 v34, 0, v34
	v_max_f32_e32 v35, 0, v35
	v_mul_f32_e32 v32, v32, v32
	v_mul_f32_e32 v33, v33, v33
	v_cvt_pk_bf16_f32 v32, v32, v33
	v_mul_f32_e32 v33, v34, v34
	v_mul_f32_e32 v34, v35, v35
	v_cvt_pk_bf16_f32 v33, v33, v34
	ds_write_b64 v112, v[32:33] offset:96
	ds_read_b128 v[32:35], v130 offset:224
	v_lshlrev_b64 v[36:37], 13, v[36:37]
	v_lshl_add_u64 v[36:37], s[42:43], 0, v[36:37]
	v_lshl_add_u64 v[36:37], v[36:37], 0, v[48:49]
	v_lshl_add_u64 v[36:37], v[36:37], 0, v[128:129]
	s_waitcnt lgkmcnt(0)
	v_fma_f32 v32, v44, v109, v32
	v_fma_f32 v33, v45, v109, v33
	v_max_f32_e32 v32, 0, v32
	v_max_f32_e32 v33, 0, v33
	v_fma_f32 v34, v46, v109, v34
	v_fmac_f32_e32 v35, v47, v109
	v_max_f32_e32 v34, 0, v34
	v_max_f32_e32 v35, 0, v35
	v_mul_f32_e32 v32, v32, v32
	v_mul_f32_e32 v33, v33, v33
	v_cvt_pk_bf16_f32 v32, v32, v33
	v_mul_f32_e32 v33, v34, v34
	v_mul_f32_e32 v34, v35, v35
	v_cvt_pk_bf16_f32 v33, v33, v34
	ds_write_b64 v112, v[32:33] offset:112
	ds_read_b128 v[32:35], v130 offset:256
	global_store_dwordx4 v[36:37], v[82:85], off
	v_or_b32_e32 v36, v106, v39
	v_ashrrev_i32_e32 v37, 31, v36
	v_lshlrev_b64 v[36:37], 13, v[36:37]
	s_waitcnt lgkmcnt(0)
	v_fma_f32 v16, v16, v109, v32
	v_fma_f32 v17, v17, v109, v33
	v_max_f32_e32 v16, 0, v16
	v_max_f32_e32 v17, 0, v17
	v_fma_f32 v18, v18, v109, v34
	v_fmac_f32_e32 v35, v19, v109
	v_max_f32_e32 v18, 0, v18
	v_max_f32_e32 v19, 0, v35
	v_mul_f32_e32 v16, v16, v16
	v_mul_f32_e32 v17, v17, v17
	v_cvt_pk_bf16_f32 v16, v16, v17
	v_mul_f32_e32 v17, v18, v18
	v_mul_f32_e32 v18, v19, v19
	v_cvt_pk_bf16_f32 v17, v17, v18
	ds_write_b64 v112, v[16:17] offset:128
	ds_read_b128 v[16:19], v130 offset:288
	v_lshl_add_u64 v[32:33], s[42:43], 0, v[36:37]
	v_lshl_add_u64 v[32:33], v[32:33], 0, v[48:49]
	v_lshl_add_u64 v[32:33], v[32:33], 0, v[128:129]
	global_store_dwordx4 v[32:33], v[98:101], off
	s_waitcnt lgkmcnt(0)
	v_fma_f32 v16, v20, v109, v16
	v_fma_f32 v17, v21, v109, v17
	v_max_f32_e32 v16, 0, v16
	v_max_f32_e32 v17, 0, v17
	v_fma_f32 v18, v22, v109, v18
	v_fmac_f32_e32 v19, v23, v109
	v_max_f32_e32 v18, 0, v18
	v_max_f32_e32 v19, 0, v19
	v_mul_f32_e32 v16, v16, v16
	v_mul_f32_e32 v17, v17, v17
	v_cvt_pk_bf16_f32 v16, v16, v17
	v_mul_f32_e32 v17, v18, v18
	v_mul_f32_e32 v18, v19, v19
	v_cvt_pk_bf16_f32 v17, v17, v18
	ds_write_b64 v112, v[16:17] offset:144
	ds_read_b128 v[16:19], v130 offset:320
	v_or_b32_e32 v22, 20, v107
	v_or_b32_e32 v20, v106, v22
	v_ashrrev_i32_e32 v21, 31, v20
	v_lshlrev_b64 v[20:21], 13, v[20:21]
	s_waitcnt lgkmcnt(0)
	v_fma_f32 v16, v24, v109, v16
	v_fma_f32 v17, v25, v109, v17
	v_max_f32_e32 v16, 0, v16
	v_max_f32_e32 v17, 0, v17
	v_fma_f32 v18, v26, v109, v18
	v_fmac_f32_e32 v19, v27, v109
	v_max_f32_e32 v18, 0, v18
	v_max_f32_e32 v19, 0, v19
	v_mul_f32_e32 v16, v16, v16
	v_mul_f32_e32 v17, v17, v17
	v_cvt_pk_bf16_f32 v16, v16, v17
	v_mul_f32_e32 v17, v18, v18
	v_mul_f32_e32 v18, v19, v19
	v_cvt_pk_bf16_f32 v17, v17, v18
	ds_write_b64 v112, v[16:17] offset:160
	ds_read_b128 v[16:19], v130 offset:352
	v_lshl_add_u64 v[20:21], s[42:43], 0, v[20:21]
	v_lshl_add_u64 v[20:21], v[20:21], 0, v[48:49]
	v_lshl_add_u64 v[20:21], v[20:21], 0, v[128:129]
	v_or_b32_e32 v23, 24, v107
	s_waitcnt lgkmcnt(0)
	v_fma_f32 v16, v28, v109, v16
	v_fma_f32 v17, v29, v109, v17
	v_max_f32_e32 v16, 0, v16
	v_max_f32_e32 v17, 0, v17
	v_fma_f32 v18, v30, v109, v18
	v_fmac_f32_e32 v19, v31, v109
	v_max_f32_e32 v18, 0, v18
	v_max_f32_e32 v19, 0, v19
	v_mul_f32_e32 v16, v16, v16
	v_mul_f32_e32 v17, v17, v17
	v_cvt_pk_bf16_f32 v16, v16, v17
	v_mul_f32_e32 v17, v18, v18
	v_mul_f32_e32 v18, v19, v19
	v_cvt_pk_bf16_f32 v17, v17, v18
	ds_write_b64 v112, v[16:17] offset:176
	ds_read_b128 v[16:19], v130 offset:384
	global_store_dwordx4 v[20:21], v[72:75], off
	v_or_b32_e32 v20, v106, v23
	v_ashrrev_i32_e32 v21, 31, v20
	v_lshlrev_b64 v[20:21], 13, v[20:21]
	s_waitcnt lgkmcnt(0)
	v_fma_f32 v0, v0, v109, v16
	v_fma_f32 v1, v1, v109, v17
	v_max_f32_e32 v0, 0, v0
	v_max_f32_e32 v1, 0, v1
	v_fma_f32 v2, v2, v109, v18
	v_fmac_f32_e32 v19, v3, v109
	v_max_f32_e32 v2, 0, v2
	v_max_f32_e32 v3, 0, v19
	v_mul_f32_e32 v0, v0, v0
	v_mul_f32_e32 v1, v1, v1
	v_cvt_pk_bf16_f32 v0, v0, v1
	v_mul_f32_e32 v1, v2, v2
	v_mul_f32_e32 v2, v3, v3
	v_cvt_pk_bf16_f32 v1, v1, v2
	ds_write_b64 v112, v[0:1] offset:192
	ds_read_b128 v[0:3], v130 offset:416
	v_lshl_add_u64 v[16:17], s[42:43], 0, v[20:21]
	v_lshl_add_u64 v[16:17], v[16:17], 0, v[48:49]
	v_lshl_add_u64 v[16:17], v[16:17], 0, v[128:129]
	global_store_dwordx4 v[16:17], v[68:71], off
	s_waitcnt lgkmcnt(0)
	v_fma_f32 v0, v4, v109, v0
	v_fma_f32 v1, v5, v109, v1
	v_max_f32_e32 v0, 0, v0
	v_max_f32_e32 v1, 0, v1
	v_fma_f32 v2, v6, v109, v2
	v_fmac_f32_e32 v3, v7, v109
	v_max_f32_e32 v2, 0, v2
	v_max_f32_e32 v3, 0, v3
	v_mul_f32_e32 v0, v0, v0
	v_mul_f32_e32 v1, v1, v1
	v_cvt_pk_bf16_f32 v0, v0, v1
	v_mul_f32_e32 v1, v2, v2
	v_mul_f32_e32 v2, v3, v3
	v_cvt_pk_bf16_f32 v1, v1, v2
	ds_write_b64 v112, v[0:1] offset:208
	ds_read_b128 v[0:3], v130 offset:448
	v_or_b32_e32 v16, 28, v107
	v_or_b32_e32 v4, v106, v16
	v_ashrrev_i32_e32 v5, 31, v4
	v_lshlrev_b64 v[4:5], 13, v[4:5]
	s_waitcnt lgkmcnt(0)
	v_fma_f32 v0, v8, v109, v0
	v_fma_f32 v1, v9, v109, v1
	v_max_f32_e32 v0, 0, v0
	v_max_f32_e32 v1, 0, v1
	v_fma_f32 v2, v10, v109, v2
	v_fmac_f32_e32 v3, v11, v109
	v_max_f32_e32 v2, 0, v2
	v_max_f32_e32 v3, 0, v3
	v_mul_f32_e32 v0, v0, v0
	v_mul_f32_e32 v1, v1, v1
	v_cvt_pk_bf16_f32 v0, v0, v1
	v_mul_f32_e32 v1, v2, v2
	v_mul_f32_e32 v2, v3, v3
	v_cvt_pk_bf16_f32 v1, v1, v2
	ds_write_b64 v112, v[0:1] offset:224
	ds_read_b128 v[0:3], v130 offset:480
	v_lshl_add_u64 v[4:5], s[42:43], 0, v[4:5]
	v_lshl_add_u64 v[4:5], v[4:5], 0, v[48:49]
	v_lshl_add_u64 v[4:5], v[4:5], 0, v[128:129]
	v_or_b32_e32 v10, 32, v106
	s_waitcnt lgkmcnt(0)
	v_fma_f32 v0, v12, v109, v0
	v_fma_f32 v1, v13, v109, v1
	v_max_f32_e32 v0, 0, v0
	v_max_f32_e32 v1, 0, v1
	v_fma_f32 v2, v14, v109, v2
	v_fmac_f32_e32 v3, v15, v109
	v_max_f32_e32 v2, 0, v2
	v_max_f32_e32 v3, 0, v3
	v_mul_f32_e32 v0, v0, v0
	v_mul_f32_e32 v1, v1, v1
	v_cvt_pk_bf16_f32 v0, v0, v1
	v_mul_f32_e32 v1, v2, v2
	v_mul_f32_e32 v2, v3, v3
	v_cvt_pk_bf16_f32 v1, v1, v2
	global_store_dwordx4 v[4:5], v[64:67], off
	ds_write_b64 v112, v[0:1] offset:240
	v_or_b32_e32 v4, v10, v107
	ds_read_b128 v[0:3], v108
	v_ashrrev_i32_e32 v5, 31, v4
	v_lshlrev_b64 v[4:5], 13, v[4:5]
	v_lshl_add_u64 v[4:5], s[42:43], 0, v[4:5]
	v_lshl_add_u64 v[4:5], v[4:5], 0, v[48:49]
	v_lshl_add_u64 v[8:9], v[4:5], 0, v[128:129]
	ds_read_b128 v[4:7], v76
	s_waitcnt lgkmcnt(1)
	global_store_dwordx4 v[8:9], v[0:3], off
	s_nop 1
	v_or_b32_e32 v0, v10, v77
	v_ashrrev_i32_e32 v1, 31, v0
	v_lshlrev_b64 v[0:1], 13, v[0:1]
	v_lshl_add_u64 v[0:1], s[42:43], 0, v[0:1]
	v_lshl_add_u64 v[0:1], v[0:1], 0, v[48:49]
	v_lshl_add_u64 v[0:1], v[0:1], 0, v[128:129]
	s_waitcnt lgkmcnt(0)
	global_store_dwordx4 v[0:1], v[4:7], off
	ds_read_b128 v[0:3], v76 offset:1088
	s_nop 0
	v_or_b32_e32 v4, v10, v56
	v_ashrrev_i32_e32 v5, 31, v4
	v_lshlrev_b64 v[4:5], 13, v[4:5]
	v_lshl_add_u64 v[4:5], s[42:43], 0, v[4:5]
	v_lshl_add_u64 v[4:5], v[4:5], 0, v[48:49]
	v_lshl_add_u64 v[8:9], v[4:5], 0, v[128:129]
	ds_read_b128 v[4:7], v76 offset:2176
	s_waitcnt lgkmcnt(1)
	global_store_dwordx4 v[8:9], v[0:3], off
	s_nop 1
	v_or_b32_e32 v0, v10, v38
	v_ashrrev_i32_e32 v1, 31, v0
	v_lshlrev_b64 v[0:1], 13, v[0:1]
	v_lshl_add_u64 v[0:1], s[42:43], 0, v[0:1]
	v_lshl_add_u64 v[0:1], v[0:1], 0, v[48:49]
	v_lshl_add_u64 v[0:1], v[0:1], 0, v[128:129]
	s_waitcnt lgkmcnt(0)
	global_store_dwordx4 v[0:1], v[4:7], off
	ds_read_b128 v[0:3], v76 offset:3264
	s_nop 0
	v_or_b32_e32 v4, v10, v39
	v_ashrrev_i32_e32 v5, 31, v4
	v_lshlrev_b64 v[4:5], 13, v[4:5]
	v_lshl_add_u64 v[4:5], s[42:43], 0, v[4:5]
	v_lshl_add_u64 v[4:5], v[4:5], 0, v[48:49]
	v_lshl_add_u64 v[8:9], v[4:5], 0, v[128:129]
	ds_read_b128 v[4:7], v76 offset:4352
	s_waitcnt lgkmcnt(1)
	global_store_dwordx4 v[8:9], v[0:3], off
	s_nop 1
	v_or_b32_e32 v0, v10, v22
	v_ashrrev_i32_e32 v1, 31, v0
	v_lshlrev_b64 v[0:1], 13, v[0:1]
	v_lshl_add_u64 v[0:1], s[42:43], 0, v[0:1]
	v_lshl_add_u64 v[0:1], v[0:1], 0, v[48:49]
	v_lshl_add_u64 v[0:1], v[0:1], 0, v[128:129]
	s_waitcnt lgkmcnt(0)
	global_store_dwordx4 v[0:1], v[4:7], off
	ds_read_b128 v[0:3], v76 offset:5440
	s_nop 0
	v_or_b32_e32 v4, v10, v23
	v_ashrrev_i32_e32 v5, 31, v4
	v_lshlrev_b64 v[4:5], 13, v[4:5]
	v_lshl_add_u64 v[4:5], s[42:43], 0, v[4:5]
	v_lshl_add_u64 v[4:5], v[4:5], 0, v[48:49]
	v_lshl_add_u64 v[8:9], v[4:5], 0, v[128:129]
	ds_read_b128 v[4:7], v76 offset:6528
	s_waitcnt lgkmcnt(1)
	global_store_dwordx4 v[8:9], v[0:3], off
	s_nop 1
	v_or_b32_e32 v0, v10, v16
	v_ashrrev_i32_e32 v1, 31, v0
	v_lshlrev_b64 v[0:1], 13, v[0:1]
	v_lshl_add_u64 v[0:1], s[42:43], 0, v[0:1]
	v_lshl_add_u64 v[0:1], v[0:1], 0, v[48:49]
	v_lshl_add_u64 v[0:1], v[0:1], 0, v[128:129]
	s_waitcnt lgkmcnt(0)
	global_store_dwordx4 v[0:1], v[4:7], off
	s_cbranch_scc0 .LBB0_1370
